# opt45: opt41 + G2 residual epilogue with full-sector f32 loads/stores (lane pairs l,l+32 exchange halves via v_permlane32_swap so each instruction covers whole 64-byte sectors)
# baseline (speedup 1.0000x reference)
; __device__ __forceinline__ unsigned cvt_pk_bf16(float lo, float hi) { f32x2_t v = {lo, hi}; bf16x2_t b = __builtin_convertvector(v, bf16x2_t); return __builtin_bit_cast(unsigned, b); }
;     __device__ __forceinline__ void operator()(const Acc& acc, const Unit& u, int wr, int wc, int fr, int fq) const {
;     ...
;                 const int row = row0 + ai * HALF + m * 16; float sq = 0.f;
; #pragma unroll
;                 for (int bj = 0; bj < 2; ++bj) {
;                     const size_t off = (size_t)row * DM + col0 + bj * HALF;
;                     const f32x4 b0 = *(const f32x4*)(base + off), b1 = *(const f32x4*)(base + off + 4);
;                     const f32x4 x0 = b0 + acc[ai][bj][m][0] * alpha, x1 = b1 + acc[ai][bj][m][1] * alpha;
;                     __builtin_nontemporal_store(x0, (f32x4*)(out + off)); __builtin_nontemporal_store(x1, (f32x4*)(out + off + 4));
;                     sq += (x0[0] * x0[0] + x0[1] * x0[1]) + (x0[2] * x0[2] + x0[3] * x0[3]) + (x1[0] * x1[0] + x1[1] * x1[1]) + (x1[2] * x1[2] + x1[3] * x1[3]);
;                     if (xb) { u32x4 w; w.x = cvt_pk_bf16(x0[0], x0[1]); w.y = cvt_pk_bf16(x0[2], x0[3]); w.z = cvt_pk_bf16(x1[0], x1[1]); w.w = cvt_pk_bf16(x1[2], x1[3]); *(u32x4*)(xb + off) = w; }
;                 }
;                 sq += __shfl_xor(sq, 16); sq += __shfl_xor(sq, 32);
;                 if (fq == 0) unsafeAtomicAdd(ss + row, sq);
.LBB0_299:
	s_and_b64 vcc, exec, s[46:47]
	s_cbranch_vccz .Lg2_epi_old
	v_lshl_add_u32 v146, s31, 8, v154
	v_lshl_or_b32 v144, s33, 8, v156
	v_lshl_add_u32 v145, v146, 10, v144
	v_lshlrev_b32_e32 v144, 2, v145
	v_lshlrev_b32_e32 v145, 1, v145
	v_lshlrev_b32_e32 v146, 2, v146
	v_xor_b32_e32 v147, 16, v162
	v_lshlrev_b32_e32 v147, 2, v147
	v_xor_b32_e32 v148, 32, v162
	v_lshlrev_b32_e32 v148, 2, v148
	v_lshrrev_b32_e32 v163, 5, v162
	v_and_b32_e32 v163, 1, v163
	v_mul_u32_u24_e32 v163, 48, v163
	v_sub_u32_e32 v163, v144, v163
	s_mov_b64 s[72:73], s[52:53]
	global_load_dwordx4 v[180:183], v163, s[72:73]
	global_load_dwordx4 v[184:187], v163, s[72:73] offset:64
	global_load_dwordx4 v[188:191], v163, s[72:73] offset:512
	global_load_dwordx4 v[192:195], v163, s[72:73] offset:576
	s_add_u32 s72, s52, 0x10000
	s_addc_u32 s73, s53, 0
	global_load_dwordx4 v[196:199], v163, s[72:73]
	global_load_dwordx4 v[200:203], v163, s[72:73] offset:64
	global_load_dwordx4 v[204:207], v163, s[72:73] offset:512
	global_load_dwordx4 v[208:211], v163, s[72:73] offset:576
	s_waitcnt vmcnt(4)
	v_permlane32_swap_b32_e32 v180, v184
	v_permlane32_swap_b32_e32 v181, v185
	v_permlane32_swap_b32_e32 v182, v186
	v_permlane32_swap_b32_e32 v183, v187
	v_permlane32_swap_b32_e32 v188, v192
	v_permlane32_swap_b32_e32 v189, v193
	v_permlane32_swap_b32_e32 v190, v194
	v_permlane32_swap_b32_e32 v191, v195
	v_fma_f32 v124, v124, 0.5, v180
	v_fma_f32 v125, v125, 0.5, v181
	v_fma_f32 v126, v126, 0.5, v182
	v_fma_f32 v127, v127, 0.5, v183
	v_fma_f32 v120, v120, 0.5, v184
	v_fma_f32 v121, v121, 0.5, v185
	v_fma_f32 v122, v122, 0.5, v186
	v_fma_f32 v123, v123, 0.5, v187
	v_fma_f32 v116, v116, 0.5, v188
	v_fma_f32 v117, v117, 0.5, v189
	v_fma_f32 v118, v118, 0.5, v190
	v_fma_f32 v119, v119, 0.5, v191
	v_fma_f32 v112, v112, 0.5, v192
	v_fma_f32 v113, v113, 0.5, v193
	v_fma_f32 v114, v114, 0.5, v194
	v_fma_f32 v115, v115, 0.5, v195
	s_add_u32 s72, s52, 0x20000
	s_addc_u32 s73, s53, 0
	global_load_dwordx4 v[212:215], v163, s[72:73]
	global_load_dwordx4 v[216:219], v163, s[72:73] offset:64
	global_load_dwordx4 v[220:223], v163, s[72:73] offset:512
	global_load_dwordx4 v[224:227], v163, s[72:73] offset:576
	v_cvt_pk_bf16_f32 v232, v124, v125
	v_cvt_pk_bf16_f32 v233, v126, v127
	v_cvt_pk_bf16_f32 v234, v120, v121
	v_cvt_pk_bf16_f32 v235, v122, v123
	v_cvt_pk_bf16_f32 v236, v116, v117
	v_cvt_pk_bf16_f32 v237, v118, v119
	v_cvt_pk_bf16_f32 v238, v112, v113
	v_cvt_pk_bf16_f32 v239, v114, v115
	v_mul_f32_e32 v228, v125, v125
	v_fmac_f32_e32 v228, v124, v124
	v_mul_f32_e32 v229, v121, v121
	v_fmac_f32_e32 v229, v120, v120
	v_mul_f32_e32 v230, v117, v117
	v_fmac_f32_e32 v230, v116, v116
	v_mul_f32_e32 v231, v113, v113
	v_fmac_f32_e32 v231, v112, v112
	v_mul_f32_e32 v240, v127, v127
	v_fmac_f32_e32 v240, v126, v126
	v_mul_f32_e32 v241, v123, v123
	v_fmac_f32_e32 v241, v122, v122
	v_mul_f32_e32 v242, v119, v119
	v_fmac_f32_e32 v242, v118, v118
	v_mul_f32_e32 v243, v115, v115
	v_fmac_f32_e32 v243, v114, v114
	v_add_f32_e32 v228, v228, v240
	v_add_f32_e32 v229, v229, v241
	v_add_f32_e32 v230, v230, v242
	v_add_f32_e32 v231, v231, v243
	v_add_f32_e32 v228, v228, v229
	v_add_f32_e32 v230, v230, v231
	v_add_f32_e32 v228, v228, v230
	v_permlane32_swap_b32_e32 v124, v120
	v_permlane32_swap_b32_e32 v125, v121
	v_permlane32_swap_b32_e32 v126, v122
	v_permlane32_swap_b32_e32 v127, v123
	v_permlane32_swap_b32_e32 v116, v112
	v_permlane32_swap_b32_e32 v117, v113
	v_permlane32_swap_b32_e32 v118, v114
	v_permlane32_swap_b32_e32 v119, v115
	s_mov_b64 s[74:75], s[90:91]
	global_store_dwordx4 v163, v[124:127], s[74:75] nt
	global_store_dwordx4 v163, v[120:123], s[74:75] offset:64 nt
	global_store_dwordx4 v163, v[116:119], s[74:75] offset:512 nt
	global_store_dwordx4 v163, v[112:115], s[74:75] offset:576 nt
	s_mov_b64 s[82:83], s[70:71]
	global_store_dwordx4 v145, v[232:235], s[82:83]
	global_store_dwordx4 v145, v[236:239], s[82:83] offset:256
	ds_bpermute_b32 v229, v147, v228
	s_waitcnt lgkmcnt(0)
	v_add_f32_e32 v228, v228, v229
	ds_bpermute_b32 v229, v148, v228
	s_waitcnt lgkmcnt(0)
	v_add_f32_e32 v228, v228, v229
	s_and_saveexec_b64 s[6:7], s[8:9]
	s_nop 1
	global_atomic_add_f32 v146, v228, s[44:45]
	s_mov_b64 exec, s[6:7]
	s_waitcnt vmcnt(11)
; __device__ __forceinline__ unsigned cvt_pk_bf16(float lo, float hi) { f32x2_t v = {lo, hi}; bf16x2_t b = __builtin_convertvector(v, bf16x2_t); return __builtin_bit_cast(unsigned, b); }
;     __device__ __forceinline__ void operator()(const Acc& acc, const Unit& u, int wr, int wc, int fr, int fq) const {
;     ...
;                 const int row = row0 + ai * HALF + m * 16; float sq = 0.f;
; #pragma unroll
;                 for (int bj = 0; bj < 2; ++bj) {
;                     const size_t off = (size_t)row * DM + col0 + bj * HALF;
;                     const f32x4 b0 = *(const f32x4*)(base + off), b1 = *(const f32x4*)(base + off + 4);
;                     const f32x4 x0 = b0 + acc[ai][bj][m][0] * alpha, x1 = b1 + acc[ai][bj][m][1] * alpha;
;                     __builtin_nontemporal_store(x0, (f32x4*)(out + off)); __builtin_nontemporal_store(x1, (f32x4*)(out + off + 4));
;                     sq += (x0[0] * x0[0] + x0[1] * x0[1]) + (x0[2] * x0[2] + x0[3] * x0[3]) + (x1[0] * x1[0] + x1[1] * x1[1]) + (x1[2] * x1[2] + x1[3] * x1[3]);
;                     if (xb) { u32x4 w; w.x = cvt_pk_bf16(x0[0], x0[1]); w.y = cvt_pk_bf16(x0[2], x0[3]); w.z = cvt_pk_bf16(x1[0], x1[1]); w.w = cvt_pk_bf16(x1[2], x1[3]); *(u32x4*)(xb + off) = w; }
;                 }
;                 sq += __shfl_xor(sq, 16); sq += __shfl_xor(sq, 32);
;                 if (fq == 0) unsafeAtomicAdd(ss + row, sq);
	v_permlane32_swap_b32_e32 v196, v200
	v_permlane32_swap_b32_e32 v197, v201
	v_permlane32_swap_b32_e32 v198, v202
	v_permlane32_swap_b32_e32 v199, v203
	v_permlane32_swap_b32_e32 v204, v208
	v_permlane32_swap_b32_e32 v205, v209
	v_permlane32_swap_b32_e32 v206, v210
	v_permlane32_swap_b32_e32 v207, v211
	v_fma_f32 v108, v108, 0.5, v196
	v_fma_f32 v109, v109, 0.5, v197
	v_fma_f32 v110, v110, 0.5, v198
	v_fma_f32 v111, v111, 0.5, v199
	v_fma_f32 v104, v104, 0.5, v200
	v_fma_f32 v105, v105, 0.5, v201
	v_fma_f32 v106, v106, 0.5, v202
	v_fma_f32 v107, v107, 0.5, v203
	v_fma_f32 v100, v100, 0.5, v204
	v_fma_f32 v101, v101, 0.5, v205
	v_fma_f32 v102, v102, 0.5, v206
	v_fma_f32 v103, v103, 0.5, v207
	v_fma_f32 v96, v96, 0.5, v208
	v_fma_f32 v97, v97, 0.5, v209
	v_fma_f32 v98, v98, 0.5, v210
	v_fma_f32 v99, v99, 0.5, v211
	s_add_u32 s72, s52, 0x30000
	s_addc_u32 s73, s53, 0
	global_load_dwordx4 v[180:183], v163, s[72:73]
	global_load_dwordx4 v[184:187], v163, s[72:73] offset:64
	global_load_dwordx4 v[188:191], v163, s[72:73] offset:512
	global_load_dwordx4 v[192:195], v163, s[72:73] offset:576
	v_cvt_pk_bf16_f32 v232, v108, v109
	v_cvt_pk_bf16_f32 v233, v110, v111
	v_cvt_pk_bf16_f32 v234, v104, v105
	v_cvt_pk_bf16_f32 v235, v106, v107
	v_cvt_pk_bf16_f32 v236, v100, v101
	v_cvt_pk_bf16_f32 v237, v102, v103
	v_cvt_pk_bf16_f32 v238, v96, v97
	v_cvt_pk_bf16_f32 v239, v98, v99
	v_mul_f32_e32 v228, v109, v109
	v_fmac_f32_e32 v228, v108, v108
	v_mul_f32_e32 v229, v105, v105
	v_fmac_f32_e32 v229, v104, v104
	v_mul_f32_e32 v230, v101, v101
	v_fmac_f32_e32 v230, v100, v100
	v_mul_f32_e32 v231, v97, v97
	v_fmac_f32_e32 v231, v96, v96
	v_mul_f32_e32 v240, v111, v111
	v_fmac_f32_e32 v240, v110, v110
	v_mul_f32_e32 v241, v107, v107
	v_fmac_f32_e32 v241, v106, v106
	v_mul_f32_e32 v242, v103, v103
	v_fmac_f32_e32 v242, v102, v102
	v_mul_f32_e32 v243, v99, v99
	v_fmac_f32_e32 v243, v98, v98
	v_add_f32_e32 v228, v228, v240
	v_add_f32_e32 v229, v229, v241
	v_add_f32_e32 v230, v230, v242
	v_add_f32_e32 v231, v231, v243
	v_add_f32_e32 v228, v228, v229
	v_add_f32_e32 v230, v230, v231
	v_add_f32_e32 v228, v228, v230
	v_permlane32_swap_b32_e32 v108, v104
	v_permlane32_swap_b32_e32 v109, v105
	v_permlane32_swap_b32_e32 v110, v106
	v_permlane32_swap_b32_e32 v111, v107
	v_permlane32_swap_b32_e32 v100, v96
	v_permlane32_swap_b32_e32 v101, v97
	v_permlane32_swap_b32_e32 v102, v98
	v_permlane32_swap_b32_e32 v103, v99
	s_add_u32 s74, s90, 0x10000
	s_addc_u32 s75, s91, 0
	global_store_dwordx4 v163, v[108:111], s[74:75] nt
	global_store_dwordx4 v163, v[104:107], s[74:75] offset:64 nt
	global_store_dwordx4 v163, v[100:103], s[74:75] offset:512 nt
	global_store_dwordx4 v163, v[96:99], s[74:75] offset:576 nt
	s_add_u32 s82, s70, 0x8000
	s_addc_u32 s83, s71, 0
	global_store_dwordx4 v145, v[232:235], s[82:83]
	global_store_dwordx4 v145, v[236:239], s[82:83] offset:256
	ds_bpermute_b32 v229, v147, v228
	s_waitcnt lgkmcnt(0)
	v_add_f32_e32 v228, v228, v229
	ds_bpermute_b32 v229, v148, v228
	s_waitcnt lgkmcnt(0)
	v_add_f32_e32 v228, v228, v229
	s_and_saveexec_b64 s[6:7], s[8:9]
	s_nop 1
	global_atomic_add_f32 v146, v228, s[44:45] offset:64
	s_mov_b64 exec, s[6:7]
	s_waitcnt vmcnt(18)
	v_permlane32_swap_b32_e32 v212, v216
	v_permlane32_swap_b32_e32 v213, v217
	v_permlane32_swap_b32_e32 v214, v218
	v_permlane32_swap_b32_e32 v215, v219
	v_permlane32_swap_b32_e32 v220, v224
	v_permlane32_swap_b32_e32 v221, v225
	v_permlane32_swap_b32_e32 v222, v226
	v_permlane32_swap_b32_e32 v223, v227
	v_fma_f32 v92, v92, 0.5, v212
	v_fma_f32 v93, v93, 0.5, v213
	v_fma_f32 v94, v94, 0.5, v214
	v_fma_f32 v95, v95, 0.5, v215
	v_fma_f32 v88, v88, 0.5, v216
	v_fma_f32 v89, v89, 0.5, v217
	v_fma_f32 v90, v90, 0.5, v218
	v_fma_f32 v91, v91, 0.5, v219
	v_fma_f32 v84, v84, 0.5, v220
	v_fma_f32 v85, v85, 0.5, v221
	v_fma_f32 v86, v86, 0.5, v222
	v_fma_f32 v87, v87, 0.5, v223
	v_fma_f32 v80, v80, 0.5, v224
	v_fma_f32 v81, v81, 0.5, v225
	v_fma_f32 v82, v82, 0.5, v226
	v_fma_f32 v83, v83, 0.5, v227
	s_add_u32 s72, s52, 0x80000
	s_addc_u32 s73, s53, 0
	global_load_dwordx4 v[196:199], v163, s[72:73]
	global_load_dwordx4 v[200:203], v163, s[72:73] offset:64
	global_load_dwordx4 v[204:207], v163, s[72:73] offset:512
	global_load_dwordx4 v[208:211], v163, s[72:73] offset:576
	v_cvt_pk_bf16_f32 v232, v92, v93
	v_cvt_pk_bf16_f32 v233, v94, v95
	v_cvt_pk_bf16_f32 v234, v88, v89
	v_cvt_pk_bf16_f32 v235, v90, v91
	v_cvt_pk_bf16_f32 v236, v84, v85
	v_cvt_pk_bf16_f32 v237, v86, v87
	v_cvt_pk_bf16_f32 v238, v80, v81
	v_cvt_pk_bf16_f32 v239, v82, v83
	v_mul_f32_e32 v228, v93, v93
	v_fmac_f32_e32 v228, v92, v92
	v_mul_f32_e32 v229, v89, v89
	v_fmac_f32_e32 v229, v88, v88
	v_mul_f32_e32 v230, v85, v85
	v_fmac_f32_e32 v230, v84, v84
	v_mul_f32_e32 v231, v81, v81
	v_fmac_f32_e32 v231, v80, v80
	v_mul_f32_e32 v240, v95, v95
	v_fmac_f32_e32 v240, v94, v94
	v_mul_f32_e32 v241, v91, v91
	v_fmac_f32_e32 v241, v90, v90
	v_mul_f32_e32 v242, v87, v87
	v_fmac_f32_e32 v242, v86, v86
	v_mul_f32_e32 v243, v83, v83
	v_fmac_f32_e32 v243, v82, v82
	v_add_f32_e32 v228, v228, v240
	v_add_f32_e32 v229, v229, v241
	v_add_f32_e32 v230, v230, v242
	v_add_f32_e32 v231, v231, v243
	v_add_f32_e32 v228, v228, v229
	v_add_f32_e32 v230, v230, v231
	v_add_f32_e32 v228, v228, v230
	v_permlane32_swap_b32_e32 v92, v88
	v_permlane32_swap_b32_e32 v93, v89
	v_permlane32_swap_b32_e32 v94, v90
	v_permlane32_swap_b32_e32 v95, v91
	v_permlane32_swap_b32_e32 v84, v80
	v_permlane32_swap_b32_e32 v85, v81
	v_permlane32_swap_b32_e32 v86, v82
	v_permlane32_swap_b32_e32 v87, v83
	s_add_u32 s74, s90, 0x20000
	s_addc_u32 s75, s91, 0
	global_store_dwordx4 v163, v[92:95], s[74:75] nt
	global_store_dwordx4 v163, v[88:91], s[74:75] offset:64 nt
	global_store_dwordx4 v163, v[84:87], s[74:75] offset:512 nt
	global_store_dwordx4 v163, v[80:83], s[74:75] offset:576 nt
	s_add_u32 s82, s70, 0x10000
	s_addc_u32 s83, s71, 0
	global_store_dwordx4 v145, v[232:235], s[82:83]
	global_store_dwordx4 v145, v[236:239], s[82:83] offset:256
	ds_bpermute_b32 v229, v147, v228
	s_waitcnt lgkmcnt(0)
; __device__ __forceinline__ unsigned cvt_pk_bf16(float lo, float hi) { f32x2_t v = {lo, hi}; bf16x2_t b = __builtin_convertvector(v, bf16x2_t); return __builtin_bit_cast(unsigned, b); }
;     __device__ __forceinline__ void operator()(const Acc& acc, const Unit& u, int wr, int wc, int fr, int fq) const {
;     ...
;                 const int row = row0 + ai * HALF + m * 16; float sq = 0.f;
; #pragma unroll
;                 for (int bj = 0; bj < 2; ++bj) {
;                     const size_t off = (size_t)row * DM + col0 + bj * HALF;
;                     const f32x4 b0 = *(const f32x4*)(base + off), b1 = *(const f32x4*)(base + off + 4);
;                     const f32x4 x0 = b0 + acc[ai][bj][m][0] * alpha, x1 = b1 + acc[ai][bj][m][1] * alpha;
;                     __builtin_nontemporal_store(x0, (f32x4*)(out + off)); __builtin_nontemporal_store(x1, (f32x4*)(out + off + 4));
;                     sq += (x0[0] * x0[0] + x0[1] * x0[1]) + (x0[2] * x0[2] + x0[3] * x0[3]) + (x1[0] * x1[0] + x1[1] * x1[1]) + (x1[2] * x1[2] + x1[3] * x1[3]);
;                     if (xb) { u32x4 w; w.x = cvt_pk_bf16(x0[0], x0[1]); w.y = cvt_pk_bf16(x0[2], x0[3]); w.z = cvt_pk_bf16(x1[0], x1[1]); w.w = cvt_pk_bf16(x1[2], x1[3]); *(u32x4*)(xb + off) = w; }
;                 }
;                 sq += __shfl_xor(sq, 16); sq += __shfl_xor(sq, 32);
;                 if (fq == 0) unsafeAtomicAdd(ss + row, sq);
	v_add_f32_e32 v228, v228, v229
	ds_bpermute_b32 v229, v148, v228
	s_waitcnt lgkmcnt(0)
	v_add_f32_e32 v228, v228, v229
	s_and_saveexec_b64 s[6:7], s[8:9]
	s_nop 1
	global_atomic_add_f32 v146, v228, s[44:45] offset:128
	s_mov_b64 exec, s[6:7]
	s_waitcnt vmcnt(18)
	v_permlane32_swap_b32_e32 v180, v184
	v_permlane32_swap_b32_e32 v181, v185
	v_permlane32_swap_b32_e32 v182, v186
	v_permlane32_swap_b32_e32 v183, v187
	v_permlane32_swap_b32_e32 v188, v192
	v_permlane32_swap_b32_e32 v189, v193
	v_permlane32_swap_b32_e32 v190, v194
	v_permlane32_swap_b32_e32 v191, v195
	v_fma_f32 v76, v76, 0.5, v180
	v_fma_f32 v77, v77, 0.5, v181
	v_fma_f32 v78, v78, 0.5, v182
	v_fma_f32 v79, v79, 0.5, v183
	v_fma_f32 v72, v72, 0.5, v184
	v_fma_f32 v73, v73, 0.5, v185
	v_fma_f32 v74, v74, 0.5, v186
	v_fma_f32 v75, v75, 0.5, v187
	v_fma_f32 v68, v68, 0.5, v188
	v_fma_f32 v69, v69, 0.5, v189
	v_fma_f32 v70, v70, 0.5, v190
	v_fma_f32 v71, v71, 0.5, v191
	v_fma_f32 v64, v64, 0.5, v192
	v_fma_f32 v65, v65, 0.5, v193
	v_fma_f32 v66, v66, 0.5, v194
	v_fma_f32 v67, v67, 0.5, v195
	s_add_u32 s72, s52, 0x90000
	s_addc_u32 s73, s53, 0
	global_load_dwordx4 v[212:215], v163, s[72:73]
	global_load_dwordx4 v[216:219], v163, s[72:73] offset:64
	global_load_dwordx4 v[220:223], v163, s[72:73] offset:512
	global_load_dwordx4 v[224:227], v163, s[72:73] offset:576
	v_cvt_pk_bf16_f32 v232, v76, v77
	v_cvt_pk_bf16_f32 v233, v78, v79
	v_cvt_pk_bf16_f32 v234, v72, v73
	v_cvt_pk_bf16_f32 v235, v74, v75
	v_cvt_pk_bf16_f32 v236, v68, v69
	v_cvt_pk_bf16_f32 v237, v70, v71
	v_cvt_pk_bf16_f32 v238, v64, v65
	v_cvt_pk_bf16_f32 v239, v66, v67
	v_mul_f32_e32 v228, v77, v77
	v_fmac_f32_e32 v228, v76, v76
	v_mul_f32_e32 v229, v73, v73
	v_fmac_f32_e32 v229, v72, v72
	v_mul_f32_e32 v230, v69, v69
	v_fmac_f32_e32 v230, v68, v68
	v_mul_f32_e32 v231, v65, v65
	v_fmac_f32_e32 v231, v64, v64
	v_mul_f32_e32 v240, v79, v79
	v_fmac_f32_e32 v240, v78, v78
	v_mul_f32_e32 v241, v75, v75
	v_fmac_f32_e32 v241, v74, v74
	v_mul_f32_e32 v242, v71, v71
	v_fmac_f32_e32 v242, v70, v70
	v_mul_f32_e32 v243, v67, v67
	v_fmac_f32_e32 v243, v66, v66
	v_add_f32_e32 v228, v228, v240
	v_add_f32_e32 v229, v229, v241
	v_add_f32_e32 v230, v230, v242
	v_add_f32_e32 v231, v231, v243
	v_add_f32_e32 v228, v228, v229
	v_add_f32_e32 v230, v230, v231
	v_add_f32_e32 v228, v228, v230
	v_permlane32_swap_b32_e32 v76, v72
	v_permlane32_swap_b32_e32 v77, v73
	v_permlane32_swap_b32_e32 v78, v74
	v_permlane32_swap_b32_e32 v79, v75
	v_permlane32_swap_b32_e32 v68, v64
	v_permlane32_swap_b32_e32 v69, v65
	v_permlane32_swap_b32_e32 v70, v66
	v_permlane32_swap_b32_e32 v71, v67
	s_add_u32 s74, s90, 0x30000
	s_addc_u32 s75, s91, 0
	global_store_dwordx4 v163, v[76:79], s[74:75] nt
	global_store_dwordx4 v163, v[72:75], s[74:75] offset:64 nt
	global_store_dwordx4 v163, v[68:71], s[74:75] offset:512 nt
	global_store_dwordx4 v163, v[64:67], s[74:75] offset:576 nt
	s_add_u32 s82, s70, 0x18000
	s_addc_u32 s83, s71, 0
	global_store_dwordx4 v145, v[232:235], s[82:83]
	global_store_dwordx4 v145, v[236:239], s[82:83] offset:256
	ds_bpermute_b32 v229, v147, v228
	s_waitcnt lgkmcnt(0)
	v_add_f32_e32 v228, v228, v229
	ds_bpermute_b32 v229, v148, v228
	s_waitcnt lgkmcnt(0)
	v_add_f32_e32 v228, v228, v229
	s_and_saveexec_b64 s[6:7], s[8:9]
	s_nop 1
	global_atomic_add_f32 v146, v228, s[44:45] offset:192
	s_mov_b64 exec, s[6:7]
	s_waitcnt vmcnt(18)
	v_permlane32_swap_b32_e32 v196, v200
	v_permlane32_swap_b32_e32 v197, v201
	v_permlane32_swap_b32_e32 v198, v202
	v_permlane32_swap_b32_e32 v199, v203
	v_permlane32_swap_b32_e32 v204, v208
	v_permlane32_swap_b32_e32 v205, v209
	v_permlane32_swap_b32_e32 v206, v210
	v_permlane32_swap_b32_e32 v207, v211
	v_fma_f32 v60, v60, 0.5, v196
	v_fma_f32 v61, v61, 0.5, v197
	v_fma_f32 v62, v62, 0.5, v198
	v_fma_f32 v63, v63, 0.5, v199
	v_fma_f32 v56, v56, 0.5, v200
	v_fma_f32 v57, v57, 0.5, v201
	v_fma_f32 v58, v58, 0.5, v202
	v_fma_f32 v59, v59, 0.5, v203
	v_fma_f32 v52, v52, 0.5, v204
	v_fma_f32 v53, v53, 0.5, v205
	v_fma_f32 v54, v54, 0.5, v206
	v_fma_f32 v55, v55, 0.5, v207
	v_fma_f32 v48, v48, 0.5, v208
	v_fma_f32 v49, v49, 0.5, v209
	v_fma_f32 v50, v50, 0.5, v210
	v_fma_f32 v51, v51, 0.5, v211
	s_add_u32 s72, s52, 0xa0000
	s_addc_u32 s73, s53, 0
	global_load_dwordx4 v[180:183], v163, s[72:73]
	global_load_dwordx4 v[184:187], v163, s[72:73] offset:64
	global_load_dwordx4 v[188:191], v163, s[72:73] offset:512
	global_load_dwordx4 v[192:195], v163, s[72:73] offset:576
	v_cvt_pk_bf16_f32 v232, v60, v61
	v_cvt_pk_bf16_f32 v233, v62, v63
	v_cvt_pk_bf16_f32 v234, v56, v57
	v_cvt_pk_bf16_f32 v235, v58, v59
	v_cvt_pk_bf16_f32 v236, v52, v53
	v_cvt_pk_bf16_f32 v237, v54, v55
	v_cvt_pk_bf16_f32 v238, v48, v49
	v_cvt_pk_bf16_f32 v239, v50, v51
	v_mul_f32_e32 v228, v61, v61
	v_fmac_f32_e32 v228, v60, v60
	v_mul_f32_e32 v229, v57, v57
	v_fmac_f32_e32 v229, v56, v56
	v_mul_f32_e32 v230, v53, v53
	v_fmac_f32_e32 v230, v52, v52
	v_mul_f32_e32 v231, v49, v49
	v_fmac_f32_e32 v231, v48, v48
	v_mul_f32_e32 v240, v63, v63
	v_fmac_f32_e32 v240, v62, v62
	v_mul_f32_e32 v241, v59, v59
	v_fmac_f32_e32 v241, v58, v58
	v_mul_f32_e32 v242, v55, v55
	v_fmac_f32_e32 v242, v54, v54
	v_mul_f32_e32 v243, v51, v51
	v_fmac_f32_e32 v243, v50, v50
	v_add_f32_e32 v228, v228, v240
	v_add_f32_e32 v229, v229, v241
	v_add_f32_e32 v230, v230, v242
	v_add_f32_e32 v231, v231, v243
	v_add_f32_e32 v228, v228, v229
	v_add_f32_e32 v230, v230, v231
	v_add_f32_e32 v228, v228, v230
	v_permlane32_swap_b32_e32 v60, v56
	v_permlane32_swap_b32_e32 v61, v57
	v_permlane32_swap_b32_e32 v62, v58
	v_permlane32_swap_b32_e32 v63, v59
	v_permlane32_swap_b32_e32 v52, v48
	v_permlane32_swap_b32_e32 v53, v49
	v_permlane32_swap_b32_e32 v54, v50
	v_permlane32_swap_b32_e32 v55, v51
	s_add_u32 s74, s90, 0x80000
	s_addc_u32 s75, s91, 0
	global_store_dwordx4 v163, v[60:63], s[74:75] nt
	global_store_dwordx4 v163, v[56:59], s[74:75] offset:64 nt
	global_store_dwordx4 v163, v[52:55], s[74:75] offset:512 nt
	global_store_dwordx4 v163, v[48:51], s[74:75] offset:576 nt
	s_add_u32 s82, s70, 0x40000
	s_addc_u32 s83, s71, 0
	global_store_dwordx4 v145, v[232:235], s[82:83]
	global_store_dwordx4 v145, v[236:239], s[82:83] offset:256
	ds_bpermute_b32 v229, v147, v228
	s_waitcnt lgkmcnt(0)
; __device__ __forceinline__ unsigned cvt_pk_bf16(float lo, float hi) { f32x2_t v = {lo, hi}; bf16x2_t b = __builtin_convertvector(v, bf16x2_t); return __builtin_bit_cast(unsigned, b); }
;     __device__ __forceinline__ void operator()(const Acc& acc, const Unit& u, int wr, int wc, int fr, int fq) const {
;     ...
;                 const int row = row0 + ai * HALF + m * 16; float sq = 0.f;
; #pragma unroll
;                 for (int bj = 0; bj < 2; ++bj) {
;                     const size_t off = (size_t)row * DM + col0 + bj * HALF;
;                     const f32x4 b0 = *(const f32x4*)(base + off), b1 = *(const f32x4*)(base + off + 4);
;                     const f32x4 x0 = b0 + acc[ai][bj][m][0] * alpha, x1 = b1 + acc[ai][bj][m][1] * alpha;
;                     __builtin_nontemporal_store(x0, (f32x4*)(out + off)); __builtin_nontemporal_store(x1, (f32x4*)(out + off + 4));
;                     sq += (x0[0] * x0[0] + x0[1] * x0[1]) + (x0[2] * x0[2] + x0[3] * x0[3]) + (x1[0] * x1[0] + x1[1] * x1[1]) + (x1[2] * x1[2] + x1[3] * x1[3]);
;                     if (xb) { u32x4 w; w.x = cvt_pk_bf16(x0[0], x0[1]); w.y = cvt_pk_bf16(x0[2], x0[3]); w.z = cvt_pk_bf16(x1[0], x1[1]); w.w = cvt_pk_bf16(x1[2], x1[3]); *(u32x4*)(xb + off) = w; }
;                 }
;                 sq += __shfl_xor(sq, 16); sq += __shfl_xor(sq, 32);
;                 if (fq == 0) unsafeAtomicAdd(ss + row, sq);
	v_add_f32_e32 v228, v228, v229
	ds_bpermute_b32 v229, v148, v228
	s_waitcnt lgkmcnt(0)
	v_add_f32_e32 v228, v228, v229
	s_and_saveexec_b64 s[6:7], s[8:9]
	s_nop 1
	global_atomic_add_f32 v146, v228, s[44:45] offset:512
	s_mov_b64 exec, s[6:7]
	s_waitcnt vmcnt(18)
	v_permlane32_swap_b32_e32 v212, v216
	v_permlane32_swap_b32_e32 v213, v217
	v_permlane32_swap_b32_e32 v214, v218
	v_permlane32_swap_b32_e32 v215, v219
	v_permlane32_swap_b32_e32 v220, v224
	v_permlane32_swap_b32_e32 v221, v225
	v_permlane32_swap_b32_e32 v222, v226
	v_permlane32_swap_b32_e32 v223, v227
	v_fma_f32 v44, v44, 0.5, v212
	v_fma_f32 v45, v45, 0.5, v213
	v_fma_f32 v46, v46, 0.5, v214
	v_fma_f32 v47, v47, 0.5, v215
	v_fma_f32 v40, v40, 0.5, v216
	v_fma_f32 v41, v41, 0.5, v217
	v_fma_f32 v42, v42, 0.5, v218
	v_fma_f32 v43, v43, 0.5, v219
	v_fma_f32 v36, v36, 0.5, v220
	v_fma_f32 v37, v37, 0.5, v221
	v_fma_f32 v38, v38, 0.5, v222
	v_fma_f32 v39, v39, 0.5, v223
	v_fma_f32 v32, v32, 0.5, v224
	v_fma_f32 v33, v33, 0.5, v225
	v_fma_f32 v34, v34, 0.5, v226
	v_fma_f32 v35, v35, 0.5, v227
	s_add_u32 s72, s52, 0xb0000
	s_addc_u32 s73, s53, 0
	global_load_dwordx4 v[196:199], v163, s[72:73]
	global_load_dwordx4 v[200:203], v163, s[72:73] offset:64
	global_load_dwordx4 v[204:207], v163, s[72:73] offset:512
	global_load_dwordx4 v[208:211], v163, s[72:73] offset:576
	v_cvt_pk_bf16_f32 v232, v44, v45
	v_cvt_pk_bf16_f32 v233, v46, v47
	v_cvt_pk_bf16_f32 v234, v40, v41
	v_cvt_pk_bf16_f32 v235, v42, v43
	v_cvt_pk_bf16_f32 v236, v36, v37
	v_cvt_pk_bf16_f32 v237, v38, v39
	v_cvt_pk_bf16_f32 v238, v32, v33
	v_cvt_pk_bf16_f32 v239, v34, v35
	v_mul_f32_e32 v228, v45, v45
	v_fmac_f32_e32 v228, v44, v44
	v_mul_f32_e32 v229, v41, v41
	v_fmac_f32_e32 v229, v40, v40
	v_mul_f32_e32 v230, v37, v37
	v_fmac_f32_e32 v230, v36, v36
	v_mul_f32_e32 v231, v33, v33
	v_fmac_f32_e32 v231, v32, v32
	v_mul_f32_e32 v240, v47, v47
	v_fmac_f32_e32 v240, v46, v46
	v_mul_f32_e32 v241, v43, v43
	v_fmac_f32_e32 v241, v42, v42
	v_mul_f32_e32 v242, v39, v39
	v_fmac_f32_e32 v242, v38, v38
	v_mul_f32_e32 v243, v35, v35
	v_fmac_f32_e32 v243, v34, v34
	v_add_f32_e32 v228, v228, v240
	v_add_f32_e32 v229, v229, v241
	v_add_f32_e32 v230, v230, v242
	v_add_f32_e32 v231, v231, v243
	v_add_f32_e32 v228, v228, v229
	v_add_f32_e32 v230, v230, v231
	v_add_f32_e32 v228, v228, v230
	v_permlane32_swap_b32_e32 v44, v40
	v_permlane32_swap_b32_e32 v45, v41
	v_permlane32_swap_b32_e32 v46, v42
	v_permlane32_swap_b32_e32 v47, v43
	v_permlane32_swap_b32_e32 v36, v32
	v_permlane32_swap_b32_e32 v37, v33
	v_permlane32_swap_b32_e32 v38, v34
	v_permlane32_swap_b32_e32 v39, v35
	s_add_u32 s74, s90, 0x90000
	s_addc_u32 s75, s91, 0
	global_store_dwordx4 v163, v[44:47], s[74:75] nt
	global_store_dwordx4 v163, v[40:43], s[74:75] offset:64 nt
	global_store_dwordx4 v163, v[36:39], s[74:75] offset:512 nt
	global_store_dwordx4 v163, v[32:35], s[74:75] offset:576 nt
	s_add_u32 s82, s70, 0x48000
	s_addc_u32 s83, s71, 0
	global_store_dwordx4 v145, v[232:235], s[82:83]
	global_store_dwordx4 v145, v[236:239], s[82:83] offset:256
	ds_bpermute_b32 v229, v147, v228
	s_waitcnt lgkmcnt(0)
	v_add_f32_e32 v228, v228, v229
	ds_bpermute_b32 v229, v148, v228
	s_waitcnt lgkmcnt(0)
	v_add_f32_e32 v228, v228, v229
	s_and_saveexec_b64 s[6:7], s[8:9]
	s_nop 1
	global_atomic_add_f32 v146, v228, s[44:45] offset:576
	s_mov_b64 exec, s[6:7]
	s_waitcnt vmcnt(18)
; __device__ __forceinline__ unsigned cvt_pk_bf16(float lo, float hi) { f32x2_t v = {lo, hi}; bf16x2_t b = __builtin_convertvector(v, bf16x2_t); return __builtin_bit_cast(unsigned, b); }
;     __device__ __forceinline__ void operator()(const Acc& acc, const Unit& u, int wr, int wc, int fr, int fq) const {
;     ...
;                 const int row = row0 + ai * HALF + m * 16; float sq = 0.f;
; #pragma unroll
;                 for (int bj = 0; bj < 2; ++bj) {
;                     const size_t off = (size_t)row * DM + col0 + bj * HALF;
;                     const f32x4 b0 = *(const f32x4*)(base + off), b1 = *(const f32x4*)(base + off + 4);
;                     const f32x4 x0 = b0 + acc[ai][bj][m][0] * alpha, x1 = b1 + acc[ai][bj][m][1] * alpha;
;                     __builtin_nontemporal_store(x0, (f32x4*)(out + off)); __builtin_nontemporal_store(x1, (f32x4*)(out + off + 4));
;                     sq += (x0[0] * x0[0] + x0[1] * x0[1]) + (x0[2] * x0[2] + x0[3] * x0[3]) + (x1[0] * x1[0] + x1[1] * x1[1]) + (x1[2] * x1[2] + x1[3] * x1[3]);
;                     if (xb) { u32x4 w; w.x = cvt_pk_bf16(x0[0], x0[1]); w.y = cvt_pk_bf16(x0[2], x0[3]); w.z = cvt_pk_bf16(x1[0], x1[1]); w.w = cvt_pk_bf16(x1[2], x1[3]); *(u32x4*)(xb + off) = w; }
;                 }
;                 sq += __shfl_xor(sq, 16); sq += __shfl_xor(sq, 32);
;                 if (fq == 0) unsafeAtomicAdd(ss + row, sq);
	v_permlane32_swap_b32_e32 v180, v184
	v_permlane32_swap_b32_e32 v181, v185
	v_permlane32_swap_b32_e32 v182, v186
	v_permlane32_swap_b32_e32 v183, v187
	v_permlane32_swap_b32_e32 v188, v192
	v_permlane32_swap_b32_e32 v189, v193
	v_permlane32_swap_b32_e32 v190, v194
	v_permlane32_swap_b32_e32 v191, v195
	v_fma_f32 v28, v28, 0.5, v180
	v_fma_f32 v29, v29, 0.5, v181
	v_fma_f32 v30, v30, 0.5, v182
	v_fma_f32 v31, v31, 0.5, v183
	v_fma_f32 v24, v24, 0.5, v184
	v_fma_f32 v25, v25, 0.5, v185
	v_fma_f32 v26, v26, 0.5, v186
	v_fma_f32 v27, v27, 0.5, v187
	v_fma_f32 v20, v20, 0.5, v188
	v_fma_f32 v21, v21, 0.5, v189
	v_fma_f32 v22, v22, 0.5, v190
	v_fma_f32 v23, v23, 0.5, v191
	v_fma_f32 v16, v16, 0.5, v192
	v_fma_f32 v17, v17, 0.5, v193
	v_fma_f32 v18, v18, 0.5, v194
	v_fma_f32 v19, v19, 0.5, v195
	v_cvt_pk_bf16_f32 v232, v28, v29
	v_cvt_pk_bf16_f32 v233, v30, v31
	v_cvt_pk_bf16_f32 v234, v24, v25
	v_cvt_pk_bf16_f32 v235, v26, v27
	v_cvt_pk_bf16_f32 v236, v20, v21
	v_cvt_pk_bf16_f32 v237, v22, v23
	v_cvt_pk_bf16_f32 v238, v16, v17
	v_cvt_pk_bf16_f32 v239, v18, v19
	v_mul_f32_e32 v228, v29, v29
	v_fmac_f32_e32 v228, v28, v28
	v_mul_f32_e32 v229, v25, v25
	v_fmac_f32_e32 v229, v24, v24
	v_mul_f32_e32 v230, v21, v21
	v_fmac_f32_e32 v230, v20, v20
	v_mul_f32_e32 v231, v17, v17
	v_fmac_f32_e32 v231, v16, v16
	v_mul_f32_e32 v240, v31, v31
	v_fmac_f32_e32 v240, v30, v30
	v_mul_f32_e32 v241, v27, v27
	v_fmac_f32_e32 v241, v26, v26
	v_mul_f32_e32 v242, v23, v23
	v_fmac_f32_e32 v242, v22, v22
	v_mul_f32_e32 v243, v19, v19
	v_fmac_f32_e32 v243, v18, v18
	v_add_f32_e32 v228, v228, v240
	v_add_f32_e32 v229, v229, v241
	v_add_f32_e32 v230, v230, v242
	v_add_f32_e32 v231, v231, v243
	v_add_f32_e32 v228, v228, v229
	v_add_f32_e32 v230, v230, v231
	v_add_f32_e32 v228, v228, v230
	v_permlane32_swap_b32_e32 v28, v24
	v_permlane32_swap_b32_e32 v29, v25
	v_permlane32_swap_b32_e32 v30, v26
	v_permlane32_swap_b32_e32 v31, v27
	v_permlane32_swap_b32_e32 v20, v16
	v_permlane32_swap_b32_e32 v21, v17
	v_permlane32_swap_b32_e32 v22, v18
	v_permlane32_swap_b32_e32 v23, v19
	s_add_u32 s74, s90, 0xa0000
	s_addc_u32 s75, s91, 0
	global_store_dwordx4 v163, v[28:31], s[74:75] nt
	global_store_dwordx4 v163, v[24:27], s[74:75] offset:64 nt
	global_store_dwordx4 v163, v[20:23], s[74:75] offset:512 nt
	global_store_dwordx4 v163, v[16:19], s[74:75] offset:576 nt
	s_add_u32 s82, s70, 0x50000
	s_addc_u32 s83, s71, 0
	global_store_dwordx4 v145, v[232:235], s[82:83]
	global_store_dwordx4 v145, v[236:239], s[82:83] offset:256
	ds_bpermute_b32 v229, v147, v228
	s_waitcnt lgkmcnt(0)
	v_add_f32_e32 v228, v228, v229
	ds_bpermute_b32 v229, v148, v228
	s_waitcnt lgkmcnt(0)
	v_add_f32_e32 v228, v228, v229
	s_and_saveexec_b64 s[6:7], s[8:9]
	s_nop 1
	global_atomic_add_f32 v146, v228, s[44:45] offset:640
	s_mov_b64 exec, s[6:7]
	s_waitcnt vmcnt(14)
	v_permlane32_swap_b32_e32 v196, v200
	v_permlane32_swap_b32_e32 v197, v201
	v_permlane32_swap_b32_e32 v198, v202
	v_permlane32_swap_b32_e32 v199, v203
	v_permlane32_swap_b32_e32 v204, v208
	v_permlane32_swap_b32_e32 v205, v209
	v_permlane32_swap_b32_e32 v206, v210
	v_permlane32_swap_b32_e32 v207, v211
	v_fma_f32 v12, v12, 0.5, v196
	v_fma_f32 v13, v13, 0.5, v197
	v_fma_f32 v14, v14, 0.5, v198
	v_fma_f32 v15, v15, 0.5, v199
	v_fma_f32 v8, v8, 0.5, v200
	v_fma_f32 v9, v9, 0.5, v201
	v_fma_f32 v10, v10, 0.5, v202
	v_fma_f32 v11, v11, 0.5, v203
	v_fma_f32 v4, v4, 0.5, v204
	v_fma_f32 v5, v5, 0.5, v205
	v_fma_f32 v6, v6, 0.5, v206
	v_fma_f32 v7, v7, 0.5, v207
	v_fma_f32 v0, v0, 0.5, v208
	v_fma_f32 v1, v1, 0.5, v209
	v_fma_f32 v2, v2, 0.5, v210
	v_fma_f32 v3, v3, 0.5, v211
	v_cvt_pk_bf16_f32 v232, v12, v13
	v_cvt_pk_bf16_f32 v233, v14, v15
	v_cvt_pk_bf16_f32 v234, v8, v9
	v_cvt_pk_bf16_f32 v235, v10, v11
	v_cvt_pk_bf16_f32 v236, v4, v5
	v_cvt_pk_bf16_f32 v237, v6, v7
	v_cvt_pk_bf16_f32 v238, v0, v1
	v_cvt_pk_bf16_f32 v239, v2, v3
	v_mul_f32_e32 v228, v13, v13
	v_fmac_f32_e32 v228, v12, v12
	v_mul_f32_e32 v229, v9, v9
	v_fmac_f32_e32 v229, v8, v8
	v_mul_f32_e32 v230, v5, v5
	v_fmac_f32_e32 v230, v4, v4
	v_mul_f32_e32 v231, v1, v1
	v_fmac_f32_e32 v231, v0, v0
	v_mul_f32_e32 v240, v15, v15
	v_fmac_f32_e32 v240, v14, v14
	v_mul_f32_e32 v241, v11, v11
	v_fmac_f32_e32 v241, v10, v10
	v_mul_f32_e32 v242, v7, v7
	v_fmac_f32_e32 v242, v6, v6
	v_mul_f32_e32 v243, v3, v3
	v_fmac_f32_e32 v243, v2, v2
	v_add_f32_e32 v228, v228, v240
	v_add_f32_e32 v229, v229, v241
	v_add_f32_e32 v230, v230, v242
	v_add_f32_e32 v231, v231, v243
	v_add_f32_e32 v228, v228, v229
	v_add_f32_e32 v230, v230, v231
	v_add_f32_e32 v228, v228, v230
	v_permlane32_swap_b32_e32 v12, v8
	v_permlane32_swap_b32_e32 v13, v9
	v_permlane32_swap_b32_e32 v14, v10
	v_permlane32_swap_b32_e32 v15, v11
	v_permlane32_swap_b32_e32 v4, v0
	v_permlane32_swap_b32_e32 v5, v1
	v_permlane32_swap_b32_e32 v6, v2
	v_permlane32_swap_b32_e32 v7, v3
	s_add_u32 s74, s90, 0xb0000
	s_addc_u32 s75, s91, 0
	global_store_dwordx4 v163, v[12:15], s[74:75] nt
	global_store_dwordx4 v163, v[8:11], s[74:75] offset:64 nt
	global_store_dwordx4 v163, v[4:7], s[74:75] offset:512 nt
	global_store_dwordx4 v163, v[0:3], s[74:75] offset:576 nt
	s_add_u32 s82, s70, 0x58000
	s_addc_u32 s83, s71, 0
	global_store_dwordx4 v145, v[232:235], s[82:83]
	global_store_dwordx4 v145, v[236:239], s[82:83] offset:256
	ds_bpermute_b32 v229, v147, v228
	s_waitcnt lgkmcnt(0)
	v_add_f32_e32 v228, v228, v229
	ds_bpermute_b32 v229, v148, v228
	s_waitcnt lgkmcnt(0)
	v_add_f32_e32 v228, v228, v229
	s_and_saveexec_b64 s[6:7], s[8:9]
	s_nop 1
	global_atomic_add_f32 v146, v228, s[44:45] offset:704
	s_mov_b64 exec, s[6:7]
	s_branch .Lg2_epi_done
